# attention tile loop rescheduled: K/V LDS fragment reads issued one step ahead of their MFMAs, exps spread 2 per MFMA gap
# speedup vs baseline: 1.0098x; 1.0098x over previous
; __device__ __forceinline__ void qk_fin(f32x16& n0, f32x16& n1, const char* Ks, const bf16x8* qr, int r32, int hi, int cbase,
;                                        const f32x16& q0, const f32x16& q1, float& l_reg, bf16x8& pa0, bf16x8& pa1, bf16x8& pa2, bf16x8& pa3) {
;   float ps = 0.f;
;   { const bf16x8 k0 = KFRAG(0, 0), k1 = KFRAG(0, 1); n0 = __builtin_amdgcn_mfma_f32_32x32x16_bf16(k0, qr[0], n0, 0, 0, 0); n1 = __builtin_amdgcn_mfma_f32_32x32x16_bf16(k1, qr[0], n1, 0, 0, 0); }
; #pragma unroll
;   for (int r = 0; r < 8; ++r) ps += q0[r];
;   PK4(q0, 0, pa0); asm volatile("" : "+v"(pa0), "+v"(ps)); SBAR();
;   { const bf16x8 k0 = KFRAG(1, 0), k1 = KFRAG(1, 1); n0 = __builtin_amdgcn_mfma_f32_32x32x16_bf16(k0, qr[1], n0, 0, 0, 0); n1 = __builtin_amdgcn_mfma_f32_32x32x16_bf16(k1, qr[1], n1, 0, 0, 0); }
; #pragma unroll
;   for (int r = 8; r < 16; ++r) ps += q0[r];
;   PK4(q0, 8, pa1); asm volatile("" : "+v"(pa1), "+v"(ps)); SBAR();
;   { const bf16x8 k0 = KFRAG(2, 0), k1 = KFRAG(2, 1); n0 = __builtin_amdgcn_mfma_f32_32x32x16_bf16(k0, qr[2], n0, 0, 0, 0); n1 = __builtin_amdgcn_mfma_f32_32x32x16_bf16(k1, qr[2], n1, 0, 0, 0); }
; #pragma unroll
;   for (int r = 0; r < 8; ++r) ps += q1[r];
;   PK4(q1, 0, pa2); asm volatile("" : "+v"(pa2), "+v"(ps)); SBAR();
;   { const bf16x8 k0 = KFRAG(3, 0), k1 = KFRAG(3, 1); n0 = __builtin_amdgcn_mfma_f32_32x32x16_bf16(k0, qr[3], n0, 0, 0, 0); n1 = __builtin_amdgcn_mfma_f32_32x32x16_bf16(k1, qr[3], n1, 0, 0, 0); }
; #pragma unroll
;   for (int r = 8; r < 16; ++r) ps += q1[r];
;   PK4(q1, 8, pa3);
;   { auto rr = __builtin_amdgcn_permlane32_swap(__float_as_uint(ps), __float_as_uint(ps), false, false); ps = __uint_as_float(rr[0]) + __uint_as_float(rr[1]); }
;   l_reg += ps; SBAR();
; }
; template <int D0> __device__ __forceinline__ void pv_one(f32x16& od, int vb, bf16x8 pa0, bf16x8 pa1, bf16x8 pa2, bf16x8 pa3) {
;   const s16x4 l0 = tr_read<v_rd_off(D0, 0, 0)>(vb), h0 = tr_read<v_rd_off(D0, 0, 1)>(vb), l1 = tr_read<v_rd_off(D0, 1, 0)>(vb), h1 = tr_read<v_rd_off(D0, 1, 1)>(vb);
;   const s16x4 l2 = tr_read<v_rd_off(D0, 2, 0)>(vb), h2 = tr_read<v_rd_off(D0, 2, 1)>(vb), l3 = tr_read<v_rd_off(D0, 3, 0)>(vb), h3 = tr_read<v_rd_off(D0, 3, 1)>(vb);
;   asm volatile("s_waitcnt lgkmcnt(0)" ::: "memory"); SBAR();
;     ...
;   od = __builtin_amdgcn_mfma_f32_32x32x16_bf16(pa0, PK(l0, h0), od, 0, 0, 0);
.LBB0_326:
	ds_read_b128 v[248:251], v241 offset:49152
	ds_read_b128 v[214:217], v241 offset:57344
	v_add_f32_e32 v179, 0, v80
	v_add_f32_e32 v179, v81, v179
	v_cvt_pk_bf16_f32 v80, v80, v81
	v_add_f32_e32 v179, v82, v179
	v_add_f32_e32 v179, v83, v179
	v_cvt_pk_bf16_f32 v81, v82, v83
	v_add_f32_e32 v179, v84, v179
	v_add_f32_e32 v179, v85, v179
	v_cvt_pk_bf16_f32 v82, v84, v85
	v_add_f32_e32 v179, v86, v179
	v_add_f32_e32 v179, v87, v179
	v_cvt_pk_bf16_f32 v83, v86, v87
	s_nop 1
	v_permlane32_swap_b32_e32 v80, v82
	v_permlane32_swap_b32_e32 v81, v83
	s_waitcnt lgkmcnt(1)
	v_mfma_f32_32x32x16_bf16 v[112:127], v[248:251], v[132:135], v[112:127]
	s_waitcnt lgkmcnt(0)
	v_mfma_f32_32x32x16_bf16 v[96:111], v[214:217], v[132:135], v[96:111]
	ds_read_b128 v[248:251], v242 offset:49152
	ds_read_b128 v[214:217], v242 offset:57344
	v_add_f32_e32 v179, v88, v179
	v_add_f32_e32 v179, v89, v179
	v_cvt_pk_bf16_f32 v84, v88, v89
	v_add_f32_e32 v179, v90, v179
	v_add_f32_e32 v179, v91, v179
	v_cvt_pk_bf16_f32 v85, v90, v91
	v_add_f32_e32 v179, v92, v179
	v_add_f32_e32 v179, v93, v179
	v_cvt_pk_bf16_f32 v86, v92, v93
	v_add_f32_e32 v179, v94, v179
	v_add_f32_e32 v179, v95, v179
	v_cvt_pk_bf16_f32 v87, v94, v95
	s_nop 1
	v_permlane32_swap_b32_e32 v84, v86
	v_permlane32_swap_b32_e32 v85, v87
	s_waitcnt lgkmcnt(1)
	v_mfma_f32_32x32x16_bf16 v[112:127], v[248:251], v[128:131], v[112:127]
	s_waitcnt lgkmcnt(0)
	v_mfma_f32_32x32x16_bf16 v[96:111], v[214:217], v[128:131], v[96:111]
	ds_read_b128 v[248:251], v243 offset:49152
	ds_read_b128 v[214:217], v243 offset:57344
	v_add_f32_e32 v179, v64, v179
	v_add_f32_e32 v179, v65, v179
	v_cvt_pk_bf16_f32 v64, v64, v65
	v_add_f32_e32 v179, v66, v179
	v_add_f32_e32 v179, v67, v179
	v_cvt_pk_bf16_f32 v65, v66, v67
	v_add_f32_e32 v179, v68, v179
	v_add_f32_e32 v179, v69, v179
	v_cvt_pk_bf16_f32 v66, v68, v69
	v_add_f32_e32 v179, v70, v179
	v_add_f32_e32 v179, v71, v179
	v_cvt_pk_bf16_f32 v67, v70, v71
	s_nop 1
	v_permlane32_swap_b32_e32 v64, v66
	v_permlane32_swap_b32_e32 v65, v67
	s_waitcnt lgkmcnt(1)
	v_mfma_f32_32x32x16_bf16 v[112:127], v[248:251], v[140:143], v[112:127]
	s_waitcnt lgkmcnt(0)
	v_mfma_f32_32x32x16_bf16 v[96:111], v[214:217], v[140:143], v[96:111]
	ds_read_b128 v[248:251], v244 offset:49152
	ds_read_b128 v[214:217], v244 offset:57344
	v_add_f32_e32 v179, v72, v179
	v_add_f32_e32 v179, v73, v179
	v_cvt_pk_bf16_f32 v68, v72, v73
	v_add_f32_e32 v179, v74, v179
	v_add_f32_e32 v179, v75, v179
	v_cvt_pk_bf16_f32 v69, v74, v75
	v_add_f32_e32 v179, v76, v179
	v_add_f32_e32 v179, v77, v179
	v_cvt_pk_bf16_f32 v70, v76, v77
	v_add_f32_e32 v179, v78, v179
	v_add_f32_e32 v247, v79, v179
	v_cvt_pk_bf16_f32 v71, v78, v79
	s_nop 1
	v_permlane32_swap_b32_e32 v68, v70
	v_permlane32_swap_b32_e32 v69, v71
	s_waitcnt lgkmcnt(1)
	v_mfma_f32_32x32x16_bf16 v[112:127], v[248:251], v[136:139], v[112:127]
	s_waitcnt lgkmcnt(0)
	v_mfma_f32_32x32x16_bf16 v[96:111], v[214:217], v[136:139], v[96:111]
	v_mov_b32_e32 v248, v247
	s_nop 1
	v_permlane32_swap_b32_e32 v247, v248
	ds_read_b64_tr_b16 v[72:73], v230 offset:0
	ds_read_b64_tr_b16 v[74:75], v230 offset:2048
	ds_read_b64_tr_b16 v[76:77], v230 offset:4096
	ds_read_b64_tr_b16 v[78:79], v230 offset:6144
	ds_read_b64_tr_b16 v[88:89], v230 offset:8192
	ds_read_b64_tr_b16 v[90:91], v230 offset:10240
	ds_read_b64_tr_b16 v[92:93], v230 offset:12288
	ds_read_b64_tr_b16 v[94:95], v230 offset:14336
	s_waitcnt lgkmcnt(4)
	v_mfma_f32_32x32x16_bf16 v[48:63], v[80:83], v[72:75], v[48:63]
	v_exp_f32_e32 v112, v112
	v_exp_f32_e32 v113, v113
	v_mfma_f32_32x32x16_bf16 v[48:63], v[84:87], v[76:79], v[48:63]
	ds_read_b64_tr_b16 v[72:73], v230 offset:512
	ds_read_b64_tr_b16 v[74:75], v230 offset:2560
	ds_read_b64_tr_b16 v[76:77], v230 offset:4608
	ds_read_b64_tr_b16 v[78:79], v230 offset:6656
	v_exp_f32_e32 v114, v114
	v_exp_f32_e32 v115, v115
	s_waitcnt lgkmcnt(4)
	v_mfma_f32_32x32x16_bf16 v[48:63], v[64:67], v[88:91], v[48:63]
	v_exp_f32_e32 v116, v116
	v_exp_f32_e32 v117, v117
	v_mfma_f32_32x32x16_bf16 v[48:63], v[68:71], v[92:95], v[48:63]
	ds_read_b64_tr_b16 v[88:89], v230 offset:8704
	ds_read_b64_tr_b16 v[90:91], v230 offset:10752
	ds_read_b64_tr_b16 v[92:93], v230 offset:12800
	ds_read_b64_tr_b16 v[94:95], v230 offset:14848
	v_exp_f32_e32 v118, v118
	v_exp_f32_e32 v119, v119
	s_waitcnt lgkmcnt(4)
	v_mfma_f32_32x32x16_bf16 v[32:47], v[80:83], v[72:75], v[32:47]
	v_exp_f32_e32 v120, v120
	v_exp_f32_e32 v121, v121
	v_mfma_f32_32x32x16_bf16 v[32:47], v[84:87], v[76:79], v[32:47]
	ds_read_b64_tr_b16 v[72:73], v230 offset:1024
	ds_read_b64_tr_b16 v[74:75], v230 offset:3072
	ds_read_b64_tr_b16 v[76:77], v230 offset:5120
	ds_read_b64_tr_b16 v[78:79], v230 offset:7168
	v_exp_f32_e32 v122, v122
	v_exp_f32_e32 v123, v123
	s_waitcnt lgkmcnt(4)
	v_mfma_f32_32x32x16_bf16 v[32:47], v[64:67], v[88:91], v[32:47]
	v_exp_f32_e32 v124, v124
	v_exp_f32_e32 v125, v125
	v_mfma_f32_32x32x16_bf16 v[32:47], v[68:71], v[92:95], v[32:47]
	ds_read_b64_tr_b16 v[88:89], v230 offset:9216
	ds_read_b64_tr_b16 v[90:91], v230 offset:11264
	ds_read_b64_tr_b16 v[92:93], v230 offset:13312
	ds_read_b64_tr_b16 v[94:95], v230 offset:15360
	v_exp_f32_e32 v126, v126
	v_exp_f32_e32 v127, v127
	s_waitcnt lgkmcnt(4)
	v_mfma_f32_32x32x16_bf16 v[16:31], v[80:83], v[72:75], v[16:31]
	v_exp_f32_e32 v96, v96
	v_exp_f32_e32 v97, v97
	v_mfma_f32_32x32x16_bf16 v[16:31], v[84:87], v[76:79], v[16:31]
	ds_read_b64_tr_b16 v[72:73], v230 offset:1536
	ds_read_b64_tr_b16 v[74:75], v230 offset:3584
	ds_read_b64_tr_b16 v[76:77], v230 offset:5632
	ds_read_b64_tr_b16 v[78:79], v230 offset:7680
	v_exp_f32_e32 v98, v98
	v_exp_f32_e32 v99, v99
	s_waitcnt lgkmcnt(4)
	v_mfma_f32_32x32x16_bf16 v[16:31], v[64:67], v[88:91], v[16:31]
	v_exp_f32_e32 v100, v100
	v_exp_f32_e32 v101, v101
	v_mfma_f32_32x32x16_bf16 v[16:31], v[68:71], v[92:95], v[16:31]
	ds_read_b64_tr_b16 v[88:89], v230 offset:9728
	ds_read_b64_tr_b16 v[90:91], v230 offset:11776
	ds_read_b64_tr_b16 v[92:93], v230 offset:13824
	ds_read_b64_tr_b16 v[94:95], v230 offset:15872
	v_exp_f32_e32 v102, v102
	v_exp_f32_e32 v103, v103
	s_waitcnt lgkmcnt(4)
	v_mfma_f32_32x32x16_bf16 v[0:15], v[80:83], v[72:75], v[0:15]
	v_exp_f32_e32 v104, v104
	v_exp_f32_e32 v105, v105
	v_mfma_f32_32x32x16_bf16 v[0:15], v[84:87], v[76:79], v[0:15]
	v_exp_f32_e32 v106, v106
	v_exp_f32_e32 v107, v107
	s_waitcnt lgkmcnt(0)
	v_mfma_f32_32x32x16_bf16 v[0:15], v[64:67], v[88:91], v[0:15]
	v_exp_f32_e32 v108, v108
	v_exp_f32_e32 v109, v109
	v_mfma_f32_32x32x16_bf16 v[0:15], v[68:71], v[92:95], v[0:15]
	v_exp_f32_e32 v110, v110
	v_exp_f32_e32 v111, v111
	s_add_i32 s76, s33, 2
	s_barrier
; #define SBAR() __builtin_amdgcn_sched_barrier(0)
; #define SLOADA(k0) do { vsA0 = *(const bf16x8*)(&Vh[(size_t)((k0) + sr) * LDP + sc]); vsA1 = *(const bf16x8*)(&Vh[(size_t)((k0) + 32 + sr) * LDP + sc]); \
;     ksA0 = *(const bf16x8*)(&Kh[(size_t)((k0) + sr) * LDP + sc]); ksA1 = *(const bf16x8*)(&Kh[(size_t)((k0) + 32 + sr) * LDP + sc]); } while (0)
; #define SWRITEA(b) do { *(bf16x8*)(V_lds + (b) * SHM_V + vst0) = vsA0; *(bf16x8*)(V_lds + (b) * SHM_V + vst1) = vsA1; const int kc = sc * 2; \
;     *(bf16x8*)(K_lds + (b) * SHM_K + KSWZ(sr, kc)) = ksA0; *(bf16x8*)(K_lds + (b) * SHM_K + KSWZ(32 + sr, kc)) = ksA1; } while (0)
; #define SWAIT() asm volatile("s_waitcnt vmcnt(4)" ::: "memory")
; __device__ __forceinline__ void attn_unit(const bf16* __restrict__ P, bf16* __restrict__ MIXIN, const float* __restrict__ gn, int seq0, int h, int q0, int nt, float kmax0, float kmax1, float slope, float lam, char* lds) {
;     ...
;     __syncthreads(); SWAIT(); SWRITEA(0); __syncthreads();
;     if (j + 3 < t1) SLOADA((j + 3) * 64); SBAR();
	s_waitcnt vmcnt(4)
	s_cmp_ge_i32 s76, s3
	s_cselect_b64 s[0:1], -1, 0
	s_and_b64 vcc, exec, s[0:1]
	ds_write_b128 v239, v[144:147]
	ds_write_b128 v240, v[152:155]
	ds_write_b128 v237, v[148:151] offset:32768
	ds_write_b128 v238, v[156:159] offset:32768
	s_waitcnt lgkmcnt(0)
	s_barrier
	s_cbranch_vccnz .LBB0_328
	v_subrev_u32_e32 v64, 32, v246
	v_mad_i64_i32 v[64:65], vcc, v64, s27, 0
	v_or_b32_e32 v64, v64, v185
	v_mad_i64_i32 v[66:67], vcc, v246, s27, 0
	v_lshl_add_u64 v[64:65], v[64:65], 1, s[24:25]
	v_or_b32_e32 v66, v66, v185
	v_lshl_add_u64 v[66:67], v[66:67], 1, s[24:25]
	global_load_dwordx4 v[144:147], v[64:65], off offset:2048
	global_load_dwordx4 v[148:151], v[64:65], off offset:1024
	global_load_dwordx4 v[152:155], v[66:67], off offset:2048
	global_load_dwordx4 v[156:159], v[66:67], off offset:1024

; __device__ __forceinline__ void qk_fin(f32x16& n0, f32x16& n1, const char* Ks, const bf16x8* qr, int r32, int hi, int cbase,
;                                        const f32x16& q0, const f32x16& q1, float& l_reg, bf16x8& pa0, bf16x8& pa1, bf16x8& pa2, bf16x8& pa3) {
;   float ps = 0.f;
;   { const bf16x8 k0 = KFRAG(0, 0), k1 = KFRAG(0, 1); n0 = __builtin_amdgcn_mfma_f32_32x32x16_bf16(k0, qr[0], n0, 0, 0, 0); n1 = __builtin_amdgcn_mfma_f32_32x32x16_bf16(k1, qr[0], n1, 0, 0, 0); }
; #pragma unroll
;   for (int r = 0; r < 8; ++r) ps += q0[r];
;   PK4(q0, 0, pa0); asm volatile("" : "+v"(pa0), "+v"(ps)); SBAR();
;   { const bf16x8 k0 = KFRAG(1, 0), k1 = KFRAG(1, 1); n0 = __builtin_amdgcn_mfma_f32_32x32x16_bf16(k0, qr[1], n0, 0, 0, 0); n1 = __builtin_amdgcn_mfma_f32_32x32x16_bf16(k1, qr[1], n1, 0, 0, 0); }
; #pragma unroll
;   for (int r = 8; r < 16; ++r) ps += q0[r];
;   PK4(q0, 8, pa1); asm volatile("" : "+v"(pa1), "+v"(ps)); SBAR();
;   { const bf16x8 k0 = KFRAG(2, 0), k1 = KFRAG(2, 1); n0 = __builtin_amdgcn_mfma_f32_32x32x16_bf16(k0, qr[2], n0, 0, 0, 0); n1 = __builtin_amdgcn_mfma_f32_32x32x16_bf16(k1, qr[2], n1, 0, 0, 0); }
; #pragma unroll
;   for (int r = 0; r < 8; ++r) ps += q1[r];
;   PK4(q1, 0, pa2); asm volatile("" : "+v"(pa2), "+v"(ps)); SBAR();
;   { const bf16x8 k0 = KFRAG(3, 0), k1 = KFRAG(3, 1); n0 = __builtin_amdgcn_mfma_f32_32x32x16_bf16(k0, qr[3], n0, 0, 0, 0); n1 = __builtin_amdgcn_mfma_f32_32x32x16_bf16(k1, qr[3], n1, 0, 0, 0); }
; #pragma unroll
;   for (int r = 8; r < 16; ++r) ps += q1[r];
;   PK4(q1, 8, pa3);
;   { auto rr = __builtin_amdgcn_permlane32_swap(__float_as_uint(ps), __float_as_uint(ps), false, false); ps = __uint_as_float(rr[0]) + __uint_as_float(rr[1]); }
;   l_reg += ps; SBAR();
; }
; template <int D0> __device__ __forceinline__ void pv_one(f32x16& od, int vb, bf16x8 pa0, bf16x8 pa1, bf16x8 pa2, bf16x8 pa3) {
;   const s16x4 l0 = tr_read<v_rd_off(D0, 0, 0)>(vb), h0 = tr_read<v_rd_off(D0, 0, 1)>(vb), l1 = tr_read<v_rd_off(D0, 1, 0)>(vb), h1 = tr_read<v_rd_off(D0, 1, 1)>(vb);
;   const s16x4 l2 = tr_read<v_rd_off(D0, 2, 0)>(vb), h2 = tr_read<v_rd_off(D0, 2, 1)>(vb), l3 = tr_read<v_rd_off(D0, 3, 0)>(vb), h3 = tr_read<v_rd_off(D0, 3, 1)>(vb);
;   asm volatile("s_waitcnt lgkmcnt(0)" ::: "memory"); SBAR();
;     ...
;   od = __builtin_amdgcn_mfma_f32_32x32x16_bf16(pa0, PK(l0, h0), od, 0, 0, 0);
.LBB0_331:
	v_add_f32_e32 v179, v247, v248
	v_add_f32_e32 v179, v231, v179
	ds_read_b128 v[214:217], v241 offset:32768
	ds_read_b128 v[248:251], v241 offset:40960
	v_add_f32_e32 v181, 0, v112
	v_add_f32_e32 v181, v113, v181
	v_cvt_pk_bf16_f32 v112, v112, v113
	v_add_f32_e32 v181, v114, v181
	v_add_f32_e32 v181, v115, v181
	v_cvt_pk_bf16_f32 v113, v114, v115
	v_add_f32_e32 v181, v116, v181
	v_add_f32_e32 v181, v117, v181
	v_cvt_pk_bf16_f32 v114, v116, v117
	v_add_f32_e32 v181, v118, v181
	v_add_f32_e32 v181, v119, v181
	v_cvt_pk_bf16_f32 v115, v118, v119
	s_nop 1
	v_permlane32_swap_b32_e32 v112, v114
	v_permlane32_swap_b32_e32 v113, v115
	s_waitcnt lgkmcnt(1)
	v_mfma_f32_32x32x16_bf16 v[80:95], v[214:217], v[132:135], v[80:95]
	s_waitcnt lgkmcnt(0)
	v_mfma_f32_32x32x16_bf16 v[64:79], v[248:251], v[132:135], v[64:79]
	ds_read_b128 v[214:217], v242 offset:32768
	ds_read_b128 v[248:251], v242 offset:40960
	v_add_f32_e32 v181, v120, v181
	v_add_f32_e32 v181, v121, v181
	v_cvt_pk_bf16_f32 v116, v120, v121
	v_add_f32_e32 v181, v122, v181
	v_add_f32_e32 v181, v123, v181
	v_cvt_pk_bf16_f32 v117, v122, v123
	v_add_f32_e32 v181, v124, v181
	v_add_f32_e32 v181, v125, v181
	v_cvt_pk_bf16_f32 v118, v124, v125
	v_add_f32_e32 v181, v126, v181
	v_add_f32_e32 v181, v127, v181
	v_cvt_pk_bf16_f32 v119, v126, v127
	s_nop 1
	v_permlane32_swap_b32_e32 v116, v118
	v_permlane32_swap_b32_e32 v117, v119
	s_waitcnt lgkmcnt(1)
	v_mfma_f32_32x32x16_bf16 v[80:95], v[214:217], v[128:131], v[80:95]
	s_waitcnt lgkmcnt(0)
	v_mfma_f32_32x32x16_bf16 v[64:79], v[248:251], v[128:131], v[64:79]
	ds_read_b128 v[214:217], v243 offset:32768
	ds_read_b128 v[248:251], v243 offset:40960
	v_add_f32_e32 v181, v96, v181
	v_add_f32_e32 v181, v97, v181
	v_cvt_pk_bf16_f32 v96, v96, v97
	v_add_f32_e32 v181, v98, v181
	v_add_f32_e32 v181, v99, v181
	v_cvt_pk_bf16_f32 v97, v98, v99
	v_add_f32_e32 v181, v100, v181
	v_add_f32_e32 v181, v101, v181
	v_cvt_pk_bf16_f32 v98, v100, v101
	v_add_f32_e32 v181, v102, v181
	v_add_f32_e32 v181, v103, v181
	v_cvt_pk_bf16_f32 v99, v102, v103
	s_nop 1
	v_permlane32_swap_b32_e32 v96, v98
	v_permlane32_swap_b32_e32 v97, v99
	s_waitcnt lgkmcnt(1)
	v_mfma_f32_32x32x16_bf16 v[80:95], v[214:217], v[140:143], v[80:95]
	s_waitcnt lgkmcnt(0)
	v_mfma_f32_32x32x16_bf16 v[64:79], v[248:251], v[140:143], v[64:79]
	ds_read_b128 v[214:217], v244 offset:32768
	ds_read_b128 v[248:251], v244 offset:40960
	v_add_f32_e32 v181, v104, v181
	v_add_f32_e32 v181, v105, v181
	v_cvt_pk_bf16_f32 v100, v104, v105
	v_add_f32_e32 v181, v106, v181
	v_add_f32_e32 v181, v107, v181
	v_cvt_pk_bf16_f32 v101, v106, v107
	v_add_f32_e32 v181, v108, v181
	v_add_f32_e32 v181, v109, v181
	v_cvt_pk_bf16_f32 v102, v108, v109
	v_add_f32_e32 v181, v110, v181
	v_add_f32_e32 v120, v111, v181
	v_cvt_pk_bf16_f32 v103, v110, v111
	s_nop 1
	v_permlane32_swap_b32_e32 v100, v102
	v_permlane32_swap_b32_e32 v101, v103
	v_mov_b32_e32 v104, v120
	s_nop 1
	v_permlane32_swap_b32_e32 v120, v104
	v_add_f32_e32 v104, v120, v104
	v_add_f32_e32 v231, v179, v104
	s_waitcnt lgkmcnt(1)
	v_mfma_f32_32x32x16_bf16 v[80:95], v[214:217], v[136:139], v[80:95]
	s_waitcnt lgkmcnt(0)
	v_mfma_f32_32x32x16_bf16 v[64:79], v[248:251], v[136:139], v[64:79]
	s_nop 0
	ds_read_b64_tr_b16 v[104:105], v245 offset:0
	ds_read_b64_tr_b16 v[106:107], v245 offset:2048
	ds_read_b64_tr_b16 v[108:109], v245 offset:4096
	ds_read_b64_tr_b16 v[110:111], v245 offset:6144
	ds_read_b64_tr_b16 v[120:121], v245 offset:8192
	ds_read_b64_tr_b16 v[122:123], v245 offset:10240
	ds_read_b64_tr_b16 v[124:125], v245 offset:12288
	ds_read_b64_tr_b16 v[126:127], v245 offset:14336
	s_waitcnt lgkmcnt(4)
	v_mfma_f32_32x32x16_bf16 v[48:63], v[112:115], v[104:107], v[48:63]
	v_exp_f32_e32 v80, v80
	v_exp_f32_e32 v81, v81
	v_mfma_f32_32x32x16_bf16 v[48:63], v[116:119], v[108:111], v[48:63]
	ds_read_b64_tr_b16 v[104:105], v245 offset:512
	ds_read_b64_tr_b16 v[106:107], v245 offset:2560
	ds_read_b64_tr_b16 v[108:109], v245 offset:4608
	ds_read_b64_tr_b16 v[110:111], v245 offset:6656
	v_exp_f32_e32 v82, v82
	v_exp_f32_e32 v83, v83
	s_waitcnt lgkmcnt(4)
	v_mfma_f32_32x32x16_bf16 v[48:63], v[96:99], v[120:123], v[48:63]
	v_exp_f32_e32 v84, v84
	v_exp_f32_e32 v85, v85
	v_mfma_f32_32x32x16_bf16 v[48:63], v[100:103], v[124:127], v[48:63]
	ds_read_b64_tr_b16 v[120:121], v245 offset:8704
	ds_read_b64_tr_b16 v[122:123], v245 offset:10752
	ds_read_b64_tr_b16 v[124:125], v245 offset:12800
	ds_read_b64_tr_b16 v[126:127], v245 offset:14848
	v_exp_f32_e32 v86, v86
	v_exp_f32_e32 v87, v87
	s_waitcnt lgkmcnt(4)
	v_mfma_f32_32x32x16_bf16 v[32:47], v[112:115], v[104:107], v[32:47]
	v_exp_f32_e32 v88, v88
	v_exp_f32_e32 v89, v89
	v_mfma_f32_32x32x16_bf16 v[32:47], v[116:119], v[108:111], v[32:47]
	ds_read_b64_tr_b16 v[104:105], v245 offset:1024
	ds_read_b64_tr_b16 v[106:107], v245 offset:3072
	ds_read_b64_tr_b16 v[108:109], v245 offset:5120
	ds_read_b64_tr_b16 v[110:111], v245 offset:7168
	v_exp_f32_e32 v90, v90
	v_exp_f32_e32 v91, v91
	s_waitcnt lgkmcnt(4)
	v_mfma_f32_32x32x16_bf16 v[32:47], v[96:99], v[120:123], v[32:47]
	v_exp_f32_e32 v92, v92
	v_exp_f32_e32 v93, v93
	v_mfma_f32_32x32x16_bf16 v[32:47], v[100:103], v[124:127], v[32:47]
	ds_read_b64_tr_b16 v[120:121], v245 offset:9216
	ds_read_b64_tr_b16 v[122:123], v245 offset:11264
	ds_read_b64_tr_b16 v[124:125], v245 offset:13312
	ds_read_b64_tr_b16 v[126:127], v245 offset:15360
	v_exp_f32_e32 v94, v94
	v_exp_f32_e32 v95, v95
	s_waitcnt lgkmcnt(4)
	v_mfma_f32_32x32x16_bf16 v[16:31], v[112:115], v[104:107], v[16:31]
	v_exp_f32_e32 v64, v64
	v_exp_f32_e32 v65, v65
	v_mfma_f32_32x32x16_bf16 v[16:31], v[116:119], v[108:111], v[16:31]
	ds_read_b64_tr_b16 v[104:105], v245 offset:1536
	ds_read_b64_tr_b16 v[106:107], v245 offset:3584
	ds_read_b64_tr_b16 v[108:109], v245 offset:5632
	ds_read_b64_tr_b16 v[110:111], v245 offset:7680
	v_exp_f32_e32 v66, v66
	v_exp_f32_e32 v67, v67
	s_waitcnt lgkmcnt(4)
	v_mfma_f32_32x32x16_bf16 v[16:31], v[96:99], v[120:123], v[16:31]
	v_exp_f32_e32 v68, v68
	v_exp_f32_e32 v69, v69
	v_mfma_f32_32x32x16_bf16 v[16:31], v[100:103], v[124:127], v[16:31]
	ds_read_b64_tr_b16 v[120:121], v245 offset:9728
	ds_read_b64_tr_b16 v[122:123], v245 offset:11776
	ds_read_b64_tr_b16 v[124:125], v245 offset:13824
	ds_read_b64_tr_b16 v[126:127], v245 offset:15872
	v_exp_f32_e32 v70, v70
	v_exp_f32_e32 v71, v71
	s_waitcnt lgkmcnt(4)
	v_mfma_f32_32x32x16_bf16 v[0:15], v[112:115], v[104:107], v[0:15]
	v_exp_f32_e32 v72, v72
	v_exp_f32_e32 v73, v73
	v_mfma_f32_32x32x16_bf16 v[0:15], v[116:119], v[108:111], v[0:15]
	v_exp_f32_e32 v74, v74
	v_exp_f32_e32 v75, v75
	s_waitcnt lgkmcnt(0)
	v_mfma_f32_32x32x16_bf16 v[0:15], v[96:99], v[120:123], v[0:15]
	v_exp_f32_e32 v76, v76
	v_exp_f32_e32 v77, v77
	v_mfma_f32_32x32x16_bf16 v[0:15], v[100:103], v[124:127], v[0:15]
	v_exp_f32_e32 v78, v78
	v_exp_f32_e32 v79, v79
	s_barrier
; #define SWRITEB(b) do { *(bf16x8*)(V_lds + (b) * SHM_V + vst0) = vsB0; *(bf16x8*)(V_lds + (b) * SHM_V + vst1) = vsB1; const int kc = sc * 2; \
;     *(bf16x8*)(K_lds + (b) * SHM_K + KSWZ(sr, kc)) = ksB0; *(bf16x8*)(K_lds + (b) * SHM_K + KSWZ(32 + sr, kc)) = ksB1; } while (0)
; #define SWAIT() asm volatile("s_waitcnt vmcnt(4)" ::: "memory")
; __device__ __forceinline__ void attn_unit(const bf16* __restrict__ P, bf16* __restrict__ MIXIN, const float* __restrict__ gn, int seq0, int h, int q0, int nt, float kmax0, float kmax1, float slope, float lam, char* lds) {
;     ...
;     __syncthreads(); SWAIT(); SWRITEB(1); __syncthreads();
;   }
	s_waitcnt vmcnt(4)
	v_add_u32_e32 v246, 0x80, v246
	s_and_b64 vcc, exec, s[0:1]
	s_waitcnt vmcnt(3)
	ds_write_b128 v239, v[160:163] offset:16384
	s_waitcnt vmcnt(1)
	ds_write_b128 v240, v[168:171] offset:16384
	ds_write_b128 v237, v[164:167] offset:49152
	s_waitcnt vmcnt(0)
	ds_write_b128 v238, v[172:175] offset:49152
	s_waitcnt lgkmcnt(0)
	s_barrier
	s_cbranch_vccnz .LBB0_336
	s_mov_b32 s33, s76
	s_add_i32 s0, s33, 1
	s_cmp_ge_i32 s0, s3
	s_cbranch_scc0 .LBB0_322
	s_branch .LBB0_323
